# 7.12 ballot trim: wave-uniform rescale/mask tests in NSA dense and selected loops feed the branch from the SGPR mask directly
# baseline (speedup 1.0000x reference)
; template <bool MASKED>
; __device__ __forceinline__ void qk_softmax(const LAS bf16_t* Kt, const bf16x8 (&qf)[3][2], float (&m)[3], f32x4 (&lacc)[3], f32x4 (&acc)[3][4], unsigned& started,
;                                            bool act, int hi, int lo, int lr, int q, bf16x8 (&pb)[3][2]) {
;     const LAS bf16_t* kbase = Kt + lr * 72 + 8 * q;
;     const int hq = hi - 4 * q, lq = lo - 4 * q;
;     f32x4 s[3][4];
;     {
;         f32x4 c0[3];
; #pragma unroll
;         for (int r = 0; r < 3; ++r) { const float nm = act ? -m[r] : -1e30f; c0[r] = (f32x4){nm, nm, nm, nm}; }
;         bf16x8 kf[2][2];
;         kf[0][0] = *(const LAS bf16x8*)(kbase); kf[0][1] = *(const LAS bf16x8*)(kbase + 32);
; #pragma unroll
;         for (int mt = 0; mt < 4; ++mt) {
;             if (mt < 3) { kf[(mt + 1) & 1][0] = *(const LAS bf16x8*)(kbase + 16 * (mt + 1) * 72); kf[(mt + 1) & 1][1] = *(const LAS bf16x8*)(kbase + 16 * (mt + 1) * 72 + 32); }
;             __builtin_amdgcn_sched_barrier(0);
; #pragma unroll
;             for (int r = 0; r < 3; ++r) { s[r][mt] = MFMA16(kf[mt & 1][0], qf[r][0], c0[r]); s[r][mt] = MFMA16(kf[mt & 1][1], qf[r][1], s[r][mt]); }
;             __builtin_amdgcn_sched_barrier(0);
;         }
;     }
;     float mx[3];
; #pragma unroll
;     for (int r = 0; r < 3; ++r) {
;         if (MASKED) {
; #pragma unroll
;             for (int mt = 0; mt < 4; ++mt)
; #pragma unroll
;                 for (int i = 0; i < 4; ++i) { s[r][mt][i] = ((16 * mt + i) <= hq && (16 * mt + i) > lq) ? s[r][mt][i] : -1e30f; }
;         }
; __device__ __forceinline__ void nsa_phase(LAS unsigned char* lds, const bf16_t* Q, const bf16_t* KVG, size_t kvg_stride, const bf16_t* kcc, const bf16_t* vcc, const float* G, bf16_t* cat,
;                                           int tid, int lane, int wave) {
;     ...
;                 __syncthreads();
;                 const int hi = hbase - 64 * n, lo = (br == 2) ? t - 512 - 64 * n : -1;
;                 const bool act = hi >= 0 && lo < 63;
;                 if (__builtin_amdgcn_ballot_w64(act) != 0ull) {
;                     bf16x8 pb[3][2];
;                     if (__builtin_amdgcn_ballot_w64(act && (hi < 63 || lo >= 0)) != 0ull) qk_softmax<true>(Kt, qf, m, lacc, acc, started, act, hi, lo, lr, q, pb);
;                     else qk_softmax<false>(Kt, qf, m, lacc, acc, started, act, hi, lo, lr, q, pb);
.LBB0_958:
	v_add_u32_e32 v97, s50, v219
	v_add_u32_e32 v96, s50, v190
	v_cndmask_b32_e64 v108, -1, v97, s[68:69]
	v_cmp_lt_i32_e32 vcc, -1, v96
	v_cmp_gt_i32_e64 s[70:71], 63, v108
	s_and_b64 vcc, vcc, s[70:71]
	s_waitcnt lgkmcnt(0)
	s_barrier
	s_cbranch_vccz .LBB0_968
	v_cmp_gt_i32_e64 s[70:71], 63, v96
	v_cmp_lt_i32_e64 s[72:73], -1, v108
	s_or_b64 s[4:5], s[70:71], s[72:73]
	s_and_b64 s[4:5], vcc, s[4:5]
	s_mov_b64 s[70:71], s[4:5]
	v_add3_u32 v230, s17, v208, v209
	v_cndmask_b32_e64 v104, v222, -v226, vcc
	v_cndmask_b32_e64 v100, v222, -v227, vcc
	v_cndmask_b32_e64 v96, v222, -v228, vcc
	s_mov_b64 vcc, s[70:71]
	s_cbranch_vccz .LBB0_969
	ds_read_b128 v[110:113], v230
	ds_read_b128 v[114:117], v230 offset:64
	ds_read_b128 v[118:121], v230 offset:2304
	ds_read_b128 v[122:125], v230 offset:2368
	v_mov_b32_e32 v105, v104
	v_mov_b32_e32 v106, v104
	v_mov_b32_e32 v101, v100
	v_mov_b32_e32 v102, v100
	v_mov_b32_e32 v103, v100
	v_mov_b32_e32 v97, v96
	v_mov_b32_e32 v98, v96
	v_mov_b32_e32 v99, v96
	v_add_u32_e32 v109, s50, v216
	v_mov_b32_e32 v107, v104
	s_waitcnt lgkmcnt(3)
	s_nop 0
	v_mfma_f32_16x16x32_bf16 v[126:129], v[110:113], v[0:3], v[104:107]
	v_mfma_f32_16x16x32_bf16 v[130:133], v[110:113], v[8:11], v[100:103]
	v_mfma_f32_16x16x32_bf16 v[110:113], v[110:113], v[16:19], v[96:99]
	s_waitcnt lgkmcnt(2)
	v_mfma_f32_16x16x32_bf16 v[126:129], v[114:117], v[4:7], v[126:129]
	v_mfma_f32_16x16x32_bf16 v[130:133], v[114:117], v[12:15], v[130:133]
	v_mfma_f32_16x16x32_bf16 v[110:113], v[114:117], v[20:23], v[110:113]
	ds_read_b128 v[114:117], v230 offset:4608
	ds_read_b128 v[134:137], v230 offset:4672
	s_waitcnt lgkmcnt(3)
	v_mfma_f32_16x16x32_bf16 v[138:141], v[118:121], v[0:3], v[104:107]
	v_mfma_f32_16x16x32_bf16 v[142:145], v[118:121], v[8:11], v[100:103]
	v_mfma_f32_16x16x32_bf16 v[118:121], v[118:121], v[16:19], v[96:99]
	s_waitcnt lgkmcnt(2)
	v_mfma_f32_16x16x32_bf16 v[138:141], v[122:125], v[4:7], v[138:141]
	v_mfma_f32_16x16x32_bf16 v[142:145], v[122:125], v[12:15], v[142:145]
	v_mfma_f32_16x16x32_bf16 v[118:121], v[122:125], v[20:23], v[118:121]
	ds_read_b128 v[122:125], v230 offset:6912
	ds_read_b128 v[146:149], v230 offset:6976
	s_waitcnt lgkmcnt(3)
	v_mfma_f32_16x16x32_bf16 v[150:153], v[114:117], v[0:3], v[104:107]
	v_mfma_f32_16x16x32_bf16 v[154:157], v[114:117], v[8:11], v[100:103]
	v_mfma_f32_16x16x32_bf16 v[114:117], v[114:117], v[16:19], v[96:99]
	s_waitcnt lgkmcnt(2)
	v_mfma_f32_16x16x32_bf16 v[150:153], v[134:137], v[4:7], v[150:153]
	v_mfma_f32_16x16x32_bf16 v[154:157], v[134:137], v[12:15], v[154:157]
	v_mfma_f32_16x16x32_bf16 v[114:117], v[134:137], v[20:23], v[114:117]
	s_waitcnt lgkmcnt(1)
	v_mfma_f32_16x16x32_bf16 v[134:137], v[122:125], v[0:3], v[104:107]
	v_mfma_f32_16x16x32_bf16 v[158:161], v[122:125], v[8:11], v[100:103]
	v_mfma_f32_16x16x32_bf16 v[122:125], v[122:125], v[16:19], v[96:99]
	s_waitcnt lgkmcnt(0)
	v_mfma_f32_16x16x32_bf16 v[134:137], v[146:149], v[4:7], v[134:137]
	v_mfma_f32_16x16x32_bf16 v[158:161], v[146:149], v[12:15], v[158:161]
	v_mfma_f32_16x16x32_bf16 v[122:125], v[146:149], v[20:23], v[122:125]
	v_sub_u32_e32 v97, v108, v210
	v_cmp_lt_i32_e64 s[72:73], -1, v109
	v_cmp_gt_i32_e64 s[74:75], 0, v97
	s_and_b64 s[72:73], s[72:73], s[74:75]
	v_cmp_lt_i32_e64 s[74:75], 0, v109
	v_cmp_gt_i32_e64 s[76:77], 1, v97
	s_and_b64 s[74:75], s[74:75], s[76:77]
	v_cmp_lt_i32_e64 s[76:77], 1, v109
	v_cmp_gt_i32_e64 s[78:79], 2, v97
	s_and_b64 s[76:77], s[76:77], s[78:79]
	v_cmp_lt_i32_e64 s[78:79], 2, v109
	v_cmp_gt_i32_e64 s[80:81], 3, v97
	s_and_b64 s[78:79], s[78:79], s[80:81]
	v_cmp_lt_i32_e64 s[80:81], 15, v109
	v_cmp_gt_i32_e64 s[84:85], 16, v97
	s_and_b64 s[80:81], s[80:81], s[84:85]
	v_cmp_lt_i32_e64 s[84:85], 16, v109
	v_cmp_gt_i32_e64 s[86:87], 17, v97
	s_and_b64 s[84:85], s[84:85], s[86:87]
	v_cmp_lt_i32_e64 s[86:87], 17, v109
	v_cmp_gt_i32_e64 s[88:89], 18, v97
	s_and_b64 s[86:87], s[86:87], s[88:89]
	v_cmp_lt_i32_e64 s[88:89], 18, v109
	v_cmp_gt_i32_e64 s[90:91], 19, v97
	s_and_b64 s[88:89], s[88:89], s[90:91]
	v_cmp_lt_i32_e64 s[90:91], 31, v109
	v_cmp_gt_i32_e64 s[92:93], 32, v97
	s_and_b64 s[90:91], s[90:91], s[92:93]
	v_cmp_lt_i32_e64 s[92:93], 32, v109
	v_cmp_gt_i32_e64 s[94:95], 33, v97
	s_and_b64 s[92:93], s[92:93], s[94:95]
	v_cmp_lt_i32_e64 s[94:95], 33, v109
	v_cmp_gt_i32_e64 s[96:97], 34, v97
	v_cmp_lt_i32_e64 s[4:5], 47, v109
	v_cmp_gt_i32_e64 s[70:71], 48, v97
	s_and_b64 s[94:95], s[94:95], s[96:97]
	v_cmp_lt_i32_e64 s[96:97], 34, v109
	v_cmp_gt_i32_e32 vcc, 35, v97
	s_and_b64 s[6:7], s[96:97], vcc
	s_and_b64 s[4:5], s[4:5], s[70:71]
	v_cmp_lt_i32_e64 s[70:71], 48, v109
	v_cmp_gt_i32_e64 s[96:97], 49, v97
	s_and_b64 s[70:71], s[70:71], s[96:97]
	v_cmp_lt_i32_e64 s[96:97], 49, v109
	v_cmp_gt_i32_e32 vcc, 50, v97
	v_cndmask_b32_e64 v102, v222, v126, s[72:73]
	v_cndmask_b32_e64 v103, v222, v127, s[74:75]
	s_and_b64 s[8:9], s[96:97], vcc
	v_cmp_lt_i32_e64 s[96:97], 50, v109
	v_cmp_gt_i32_e32 vcc, 51, v97
	v_cndmask_b32_e64 v166, v222, v129, s[78:79]
	v_cndmask_b32_e64 v167, v222, v138, s[80:81]
	v_cndmask_b32_e64 v168, v222, v139, s[84:85]
	v_cndmask_b32_e64 v172, v222, v151, s[92:93]
	v_cndmask_b32_e64 v173, v222, v152, s[94:95]
	v_cndmask_b32_e64 v174, v222, v153, s[6:7]
	v_cndmask_b32_e64 v175, v222, v134, s[4:5]
	v_cndmask_b32_e64 v176, v222, v135, s[70:71]
	v_cndmask_b32_e64 v177, v222, v136, s[8:9]
	s_and_b64 vcc, s[96:97], vcc
	v_max_f32_e32 v97, v103, v103
	v_max_f32_e32 v98, v102, v102
	v_cndmask_b32_e64 v105, v222, v128, s[76:77]
	v_cndmask_b32_e64 v169, v222, v140, s[86:87]
	v_cndmask_b32_e64 v170, v222, v141, s[88:89]
	v_cndmask_b32_e64 v171, v222, v150, s[90:91]
; __device__ __forceinline__ float xmax16(float v) { const auto r = __builtin_amdgcn_permlane16_swap(__float_as_uint(v), __float_as_uint(v), false, false); return fmaxf(__uint_as_float(r[0]), __uint_as_float(r[1])); }
; __device__ __forceinline__ float xmax32(float v) { const auto r = __builtin_amdgcn_permlane32_swap(__float_as_uint(v), __float_as_uint(v), false, false); return fmaxf(__uint_as_float(r[0]), __uint_as_float(r[1])); }
; template <bool MASKED>
; __device__ __forceinline__ void qk_softmax(const LAS bf16_t* Kt, const bf16x8 (&qf)[3][2], float (&m)[3], f32x4 (&lacc)[3], f32x4 (&acc)[3][4], unsigned& started,
;                                            bool act, int hi, int lo, int lr, int q, bf16x8 (&pb)[3][2]) {
;     ...
;     float mx[3];
; #pragma unroll
;     for (int r = 0; r < 3; ++r) {
;         if (MASKED) {
; #pragma unroll
;             for (int mt = 0; mt < 4; ++mt)
; #pragma unroll
;                 for (int i = 0; i < 4; ++i) { s[r][mt][i] = ((16 * mt + i) <= hq && (16 * mt + i) > lq) ? s[r][mt][i] : -1e30f; }
;         }
;         mx[r] = fmaxf(fmaxf(fmaxf(fmaxf(fmaxf(s[r][0][0], s[r][0][1]), s[r][0][2]), fmaxf(fmaxf(s[r][0][3], s[r][1][0]), s[r][1][1])), fmaxf(fmaxf(s[r][1][2], s[r][1][3]), s[r][2][0])), fmaxf(fmaxf(fmaxf(fmaxf(s[r][2][1], s[r][2][2]), s[r][2][3]), fmaxf(fmaxf(s[r][3][0], s[r][3][1]), s[r][3][2])), s[r][3][3]));
;     }
; #pragma unroll
;     for (int r = 0; r < 3; ++r) mx[r] = pg8::xmax16(mx[r]);
; #pragma unroll
;     for (int r = 0; r < 3; ++r) mx[r] = pg8::xmax32(mx[r]);
;     bool need[3]; bool anyneed = false;
; #pragma unroll
;     for (int r = 0; r < 3; ++r) { const bool st = ((started >> r) & 1u) != 0u; need[r] = (mx[r] > -1e29f) && (!st || mx[r] > RESC_THR); anyneed = anyneed || need[r]; }
;     if (__builtin_amdgcn_ballot_w64(anyneed) != 0ull) {
	v_cndmask_b32_e32 v178, v222, v137, vcc
	v_max_f32_e32 v97, v98, v97
	v_max3_f32 v98, v166, v167, v168
	v_max3_f32 v99, v172, v173, v174
	v_max3_f32 v101, v175, v176, v177
	v_max3_f32 v97, v97, v105, v98
	v_max3_f32 v98, v169, v170, v171
	v_max3_f32 v99, v99, v101, v178
	v_cndmask_b32_e64 v183, v222, v130, s[72:73]
	v_cndmask_b32_e64 v184, v222, v131, s[74:75]
	v_max3_f32 v97, v97, v98, v99
	v_cndmask_b32_e64 v186, v222, v133, s[78:79]
	v_cndmask_b32_e64 v179, v222, v142, s[80:81]
	v_cndmask_b32_e64 v180, v222, v143, s[84:85]
	v_cndmask_b32_e64 v188, v222, v155, s[92:93]
	v_cndmask_b32_e64 v189, v222, v156, s[94:95]
	v_cndmask_b32_e64 v231, v222, v157, s[6:7]
	v_cndmask_b32_e64 v232, v222, v158, s[4:5]
	v_cndmask_b32_e64 v233, v222, v159, s[70:71]
	v_cndmask_b32_e64 v234, v222, v160, s[8:9]
	v_max_f32_e32 v98, v184, v184
	v_max_f32_e32 v99, v183, v183
	v_cndmask_b32_e64 v185, v222, v132, s[76:77]
	v_cndmask_b32_e64 v181, v222, v144, s[86:87]
	v_cndmask_b32_e64 v182, v222, v145, s[88:89]
	v_cndmask_b32_e64 v187, v222, v154, s[90:91]
	v_cndmask_b32_e32 v235, v222, v161, vcc
	v_max_f32_e32 v98, v99, v98
	v_max3_f32 v99, v186, v179, v180
	v_max3_f32 v101, v188, v189, v231
	v_max3_f32 v106, v232, v233, v234
	v_max3_f32 v98, v98, v185, v99
	v_max3_f32 v99, v181, v182, v187
	v_max3_f32 v101, v101, v106, v235
	v_cndmask_b32_e64 v236, v222, v110, s[72:73]
	v_cndmask_b32_e64 v237, v222, v111, s[74:75]
	v_max3_f32 v98, v98, v99, v101
	v_cndmask_b32_e64 v239, v222, v113, s[78:79]
	v_cndmask_b32_e64 v240, v222, v118, s[80:81]
	v_cndmask_b32_e64 v241, v222, v119, s[84:85]
	v_cndmask_b32_e64 v246, v222, v115, s[92:93]
	v_cndmask_b32_e64 v247, v222, v116, s[94:95]
	v_cndmask_b32_e64 v248, v222, v117, s[6:7]
	v_cndmask_b32_e64 v249, v222, v122, s[4:5]
	v_cndmask_b32_e64 v250, v222, v123, s[70:71]
	v_cndmask_b32_e64 v251, v222, v124, s[8:9]
	v_max_f32_e32 v99, v237, v237
	v_max_f32_e32 v101, v236, v236
	v_cndmask_b32_e64 v238, v222, v112, s[76:77]
	v_cndmask_b32_e64 v242, v222, v120, s[86:87]
	v_cndmask_b32_e64 v243, v222, v121, s[88:89]
	v_cndmask_b32_e64 v245, v222, v114, s[90:91]
	v_cndmask_b32_e32 v244, v222, v125, vcc
	v_max_f32_e32 v99, v101, v99
	v_max3_f32 v101, v239, v240, v241
	v_max3_f32 v106, v246, v247, v248
	v_max3_f32 v107, v249, v250, v251
	v_max3_f32 v99, v99, v238, v101
	v_max3_f32 v101, v242, v243, v245
	v_max3_f32 v106, v106, v107, v244
	v_max3_f32 v99, v99, v101, v106
	v_mov_b32_e32 v101, v97
	s_nop 1
	v_permlane16_swap_b32_e32 v97, v101
	v_max_f32_e32 v101, v101, v101
	v_max_f32_e32 v97, v97, v97
	v_max_f32_e32 v97, v97, v101
	v_mov_b32_e32 v101, v98
	s_nop 1
	v_permlane16_swap_b32_e32 v98, v101
	v_max_f32_e32 v101, v101, v101
	v_max_f32_e32 v98, v98, v98
	v_max_f32_e32 v98, v98, v101
	v_mov_b32_e32 v101, v99
	s_nop 1
	v_permlane16_swap_b32_e32 v99, v101
	v_max_f32_e32 v101, v101, v101
	v_max_f32_e32 v99, v99, v99
	v_max_f32_e32 v99, v99, v101
	v_mov_b32_e32 v101, v97
	s_nop 1
	v_permlane32_swap_b32_e32 v97, v101
	v_max_f32_e32 v101, v101, v101
	v_max_f32_e32 v97, v97, v97
	v_max_f32_e32 v97, v97, v101
	v_mov_b32_e32 v106, v98
	v_mov_b32_e32 v101, v99
	s_mov_b32 s88, 0x41000000
	v_permlane32_swap_b32_e32 v98, v106
	v_permlane32_swap_b32_e32 v99, v101
	v_cmp_lt_f32_e32 vcc, s33, v97
	s_mov_b64 s[6:7], 0
	s_mov_b64 s[8:9], 0
	s_and_saveexec_b64 s[18:19], vcc
	v_and_b32_e32 v107, 1, v229
	v_cmp_eq_u32_e32 vcc, 0, v107
	v_cmp_lt_f32_e64 s[4:5], s88, v97
	s_or_b64 s[4:5], vcc, s[4:5]
	s_and_b64 s[8:9], s[4:5], exec
	s_or_b64 exec, exec, s[18:19]
	v_max_f32_e32 v98, v98, v98
	v_max_f32_e32 v106, v106, v106
	v_max_f32_e32 v98, v98, v106
	v_cmp_lt_f32_e32 vcc, s33, v98
	s_and_saveexec_b64 s[18:19], vcc
	v_and_b32_e32 v106, 2, v229
	v_cmp_eq_u32_e32 vcc, 0, v106
	v_cmp_lt_f32_e64 s[4:5], s88, v98
	s_or_b64 s[4:5], vcc, s[4:5]
	s_and_b64 s[6:7], s[4:5], exec
	s_or_b64 exec, exec, s[18:19]
	v_max_f32_e32 v99, v99, v99
	v_max_f32_e32 v101, v101, v101
	v_max_f32_e32 v99, v99, v101
	v_cmp_lt_f32_e32 vcc, s33, v99
	s_mov_b64 s[4:5], 0
	s_and_saveexec_b64 s[18:19], vcc
	v_and_b32_e32 v101, 4, v229
	v_cmp_eq_u32_e32 vcc, 0, v101
	v_cmp_lt_f32_e64 s[4:5], s88, v99
	s_or_b64 s[4:5], vcc, s[4:5]
	s_and_b64 s[4:5], s[4:5], exec
	s_or_b64 exec, exec, s[18:19]
	s_or_b64 s[18:19], s[8:9], s[6:7]
	s_or_b64 s[18:19], s[18:19], s[4:5]
	s_and_b64 vcc, exec, s[18:19]
	s_cbranch_vccz .LBB0_970
; template <bool MASKED>
; __device__ __forceinline__ void qk_softmax(const LAS bf16_t* Kt, const bf16x8 (&qf)[3][2], float (&m)[3], f32x4 (&lacc)[3], f32x4 (&acc)[3][4], unsigned& started,
;                                            bool act, int hi, int lo, int lr, int q, bf16x8 (&pb)[3][2]) {
;     ...
; #pragma unroll
;         for (int r = 0; r < 3; ++r) {
;             const bool st = ((started >> r) & 1u) != 0u;
;             const float dl = need[r] ? mx[r] : 0.f;
;             const float alpha = need[r] ? (st ? __builtin_amdgcn_exp2f(-dl) : 0.f) : 1.f;
;             m[r] += dl;
; #pragma unroll
;             for (int mt = 0; mt < 4; ++mt) s[r][mt] = s[r][mt] - dl;
;             lacc[r] = lacc[r] * alpha;
; #pragma unroll
;             for (int dt = 0; dt < 4; ++dt) acc[r][dt] = acc[r][dt] * alpha;
;             if (need[r]) started |= (1u << r);
;         }
;     }
	v_cndmask_b32_e64 v101, 0, v97, s[8:9]
	v_exp_f32_e64 v106, -v101
	v_add_f32_e32 v97, v226, v101
	v_sub_f32_e32 v102, v102, v101
	v_sub_f32_e32 v103, v103, v101
	v_sub_f32_e32 v105, v105, v101
	v_sub_f32_e32 v166, v166, v101
	v_sub_f32_e32 v167, v167, v101
	v_sub_f32_e32 v168, v168, v101
	v_sub_f32_e32 v169, v169, v101
	v_sub_f32_e32 v170, v170, v101
	v_sub_f32_e32 v171, v171, v101
	v_sub_f32_e32 v172, v172, v101
	v_sub_f32_e32 v173, v173, v101
	v_sub_f32_e32 v174, v174, v101
	v_sub_f32_e32 v175, v175, v101
	v_sub_f32_e32 v176, v176, v101
	v_sub_f32_e32 v177, v177, v101
	v_sub_f32_e32 v178, v178, v101
	v_cndmask_b32_e64 v101, 0, 1, s[8:9]
	v_cndmask_b32_e64 v126, 0, v98, s[6:7]
	v_exp_f32_e64 v98, -v126
	v_or_b32_e32 v101, v229, v101
	v_cndmask_b32_e64 v147, 0, v99, s[4:5]
	v_and_b32_e32 v107, 1, v229
	v_or_b32_e32 v146, 2, v101
	v_exp_f32_e64 v99, -v147
	v_cmp_eq_u32_e32 vcc, 1, v107
	v_and_b32_e32 v127, 2, v229
	v_cndmask_b32_e64 v101, v101, v146, s[6:7]
	v_cndmask_b32_e32 v106, 0, v106, vcc
	v_cmp_ne_u32_e32 vcc, 0, v127
	v_and_b32_e32 v146, 4, v101
	v_cndmask_b32_e64 v106, 1.0, v106, s[8:9]
	v_cndmask_b32_e32 v127, 0, v98, vcc
	v_cmp_ne_u32_e32 vcc, 0, v146
	v_add_f32_e32 v98, v227, v126
	v_sub_f32_e32 v183, v183, v126
	v_cndmask_b32_e32 v146, 0, v99, vcc
	v_sub_f32_e32 v184, v184, v126
	v_sub_f32_e32 v185, v185, v126
	v_sub_f32_e32 v186, v186, v126
	v_sub_f32_e32 v179, v179, v126
	v_sub_f32_e32 v180, v180, v126
	v_sub_f32_e32 v181, v181, v126
	v_sub_f32_e32 v182, v182, v126
	v_sub_f32_e32 v187, v187, v126
	v_sub_f32_e32 v188, v188, v126
	v_sub_f32_e32 v189, v189, v126
	v_sub_f32_e32 v231, v231, v126
	v_sub_f32_e32 v232, v232, v126
	v_sub_f32_e32 v233, v233, v126
	v_sub_f32_e32 v234, v234, v126
	v_sub_f32_e32 v235, v235, v126
	v_cndmask_b32_e64 v126, 1.0, v127, s[6:7]
	v_cndmask_b32_e64 v146, 1.0, v146, s[4:5]
	v_or_b32_e32 v252, 4, v101
	v_pk_mul_f32 v[120:121], v[94:95], v[106:107] op_sel_hi:[1,0]
	v_pk_mul_f32 v[118:119], v[92:93], v[106:107] op_sel_hi:[1,0]
	v_pk_mul_f32 v[124:125], v[70:71], v[106:107] op_sel_hi:[1,0]
	v_pk_mul_f32 v[122:123], v[68:69], v[106:107] op_sel_hi:[1,0]
	v_pk_mul_f32 v[116:117], v[66:67], v[106:107] op_sel_hi:[1,0]
	v_pk_mul_f32 v[114:115], v[64:65], v[106:107] op_sel_hi:[1,0]
	v_pk_mul_f32 v[112:113], v[62:63], v[106:107] op_sel_hi:[1,0]
	v_pk_mul_f32 v[110:111], v[60:61], v[106:107] op_sel_hi:[1,0]
	v_pk_mul_f32 v[108:109], v[58:59], v[106:107] op_sel_hi:[1,0]
	v_pk_mul_f32 v[106:107], v[56:57], v[106:107] op_sel_hi:[1,0]
	v_pk_mul_f32 v[140:141], v[90:91], v[126:127] op_sel_hi:[1,0]
	v_pk_mul_f32 v[138:139], v[88:89], v[126:127] op_sel_hi:[1,0]
	v_pk_mul_f32 v[144:145], v[54:55], v[126:127] op_sel_hi:[1,0]
	v_pk_mul_f32 v[142:143], v[52:53], v[126:127] op_sel_hi:[1,0]
	v_pk_mul_f32 v[136:137], v[50:51], v[126:127] op_sel_hi:[1,0]
	v_pk_mul_f32 v[134:135], v[48:49], v[126:127] op_sel_hi:[1,0]
	v_pk_mul_f32 v[132:133], v[46:47], v[126:127] op_sel_hi:[1,0]
	v_pk_mul_f32 v[130:131], v[44:45], v[126:127] op_sel_hi:[1,0]
	v_pk_mul_f32 v[128:129], v[42:43], v[126:127] op_sel_hi:[1,0]
	v_pk_mul_f32 v[126:127], v[40:41], v[126:127] op_sel_hi:[1,0]
	v_add_f32_e32 v99, v228, v147
	v_sub_f32_e32 v236, v236, v147
	v_sub_f32_e32 v237, v237, v147
	v_sub_f32_e32 v238, v238, v147
	v_sub_f32_e32 v239, v239, v147
	v_sub_f32_e32 v240, v240, v147
	v_sub_f32_e32 v241, v241, v147
	v_sub_f32_e32 v242, v242, v147
	v_sub_f32_e32 v243, v243, v147
	v_sub_f32_e32 v245, v245, v147
	v_sub_f32_e32 v246, v246, v147
	v_sub_f32_e32 v247, v247, v147
	v_sub_f32_e32 v248, v248, v147
	v_sub_f32_e32 v249, v249, v147
	v_sub_f32_e32 v250, v250, v147
	v_sub_f32_e32 v251, v251, v147
	v_sub_f32_e32 v244, v244, v147
	v_pk_mul_f32 v[152:153], v[86:87], v[146:147] op_sel_hi:[1,0]
	v_pk_mul_f32 v[150:151], v[84:85], v[146:147] op_sel_hi:[1,0]
	v_pk_mul_f32 v[164:165], v[38:39], v[146:147] op_sel_hi:[1,0]
	v_pk_mul_f32 v[162:163], v[36:37], v[146:147] op_sel_hi:[1,0]
	v_pk_mul_f32 v[160:161], v[34:35], v[146:147] op_sel_hi:[1,0]
	v_pk_mul_f32 v[158:159], v[32:33], v[146:147] op_sel_hi:[1,0]
	v_pk_mul_f32 v[156:157], v[30:31], v[146:147] op_sel_hi:[1,0]
	v_pk_mul_f32 v[154:155], v[28:29], v[146:147] op_sel_hi:[1,0]
	v_pk_mul_f32 v[148:149], v[26:27], v[146:147] op_sel_hi:[1,0]
	v_pk_mul_f32 v[146:147], v[24:25], v[146:147] op_sel_hi:[1,0]
	v_cndmask_b32_e64 v101, v101, v252, s[4:5]
	s_branch .LBB0_971

; #define LAS __attribute__((address_space(3)))
; template <bool MASKED>
; __device__ __forceinline__ void qk_softmax(const LAS bf16_t* Kt, const bf16x8 (&qf)[3][2], float (&m)[3], f32x4 (&lacc)[3], f32x4 (&acc)[3][4], unsigned& started,
;                                            bool act, int hi, int lo, int lr, int q, bf16x8 (&pb)[3][2]) {
;     const LAS bf16_t* kbase = Kt + lr * 72 + 8 * q;
;     const int hq = hi - 4 * q, lq = lo - 4 * q;
;     f32x4 s[3][4];
;     {
;         f32x4 c0[3];
; #pragma unroll
;         for (int r = 0; r < 3; ++r) { const float nm = act ? -m[r] : -1e30f; c0[r] = (f32x4){nm, nm, nm, nm}; }
;         bf16x8 kf[2][2];
;         kf[0][0] = *(const LAS bf16x8*)(kbase); kf[0][1] = *(const LAS bf16x8*)(kbase + 32);
; #pragma unroll
;         for (int mt = 0; mt < 4; ++mt) {
;             if (mt < 3) { kf[(mt + 1) & 1][0] = *(const LAS bf16x8*)(kbase + 16 * (mt + 1) * 72); kf[(mt + 1) & 1][1] = *(const LAS bf16x8*)(kbase + 16 * (mt + 1) * 72 + 32); }
;             __builtin_amdgcn_sched_barrier(0);
; #pragma unroll
;             for (int r = 0; r < 3; ++r) { s[r][mt] = MFMA16(kf[mt & 1][0], qf[r][0], c0[r]); s[r][mt] = MFMA16(kf[mt & 1][1], qf[r][1], s[r][mt]); }
;             __builtin_amdgcn_sched_barrier(0);
;         }
;     }
;     float mx[3];
; #pragma unroll
;     for (int r = 0; r < 3; ++r) {
;         if (MASKED) {
; #pragma unroll
;             for (int mt = 0; mt < 4; ++mt)
; #pragma unroll
;                 for (int i = 0; i < 4; ++i) { s[r][mt][i] = ((16 * mt + i) <= hq && (16 * mt + i) > lq) ? s[r][mt][i] : -1e30f; }
;         }
;         mx[r] = fmaxf(fmaxf(fmaxf(fmaxf(fmaxf(s[r][0][0], s[r][0][1]), s[r][0][2]), fmaxf(fmaxf(s[r][0][3], s[r][1][0]), s[r][1][1])), fmaxf(fmaxf(s[r][1][2], s[r][1][3]), s[r][2][0])), fmaxf(fmaxf(fmaxf(fmaxf(s[r][2][1], s[r][2][2]), s[r][2][3]), fmaxf(fmaxf(s[r][3][0], s[r][3][1]), s[r][3][2])), s[r][3][3]));
;     }
; #pragma unroll
;     for (int r = 0; r < 3; ++r) mx[r] = pg8::xmax16(mx[r]);
; #pragma unroll
;     for (int r = 0; r < 3; ++r) mx[r] = pg8::xmax32(mx[r]);
;     bool need[3]; bool anyneed = false;
; #pragma unroll
;     for (int r = 0; r < 3; ++r) { const bool st = ((started >> r) & 1u) != 0u; need[r] = (mx[r] > -1e29f) && (!st || mx[r] > RESC_THR); anyneed = anyneed || need[r]; }
;     if (__builtin_amdgcn_ballot_w64(anyneed) != 0ull) {
.LBB0_972:
	ds_read_b128 v[108:111], v230
	ds_read_b128 v[112:115], v230 offset:64
	ds_read_b128 v[116:119], v230 offset:2304
	ds_read_b128 v[128:131], v230 offset:2368
	v_mov_b32_e32 v105, v104
	v_mov_b32_e32 v106, v104
	v_mov_b32_e32 v107, v104
	v_mov_b32_e32 v101, v100
	v_mov_b32_e32 v102, v100
	v_mov_b32_e32 v103, v100
	v_mov_b32_e32 v97, v96
	v_mov_b32_e32 v98, v96
	v_mov_b32_e32 v99, v96
	s_waitcnt lgkmcnt(3)
	v_mfma_f32_16x16x32_bf16 v[120:123], v[108:111], v[0:3], v[104:107]
	s_waitcnt lgkmcnt(2)
	v_mfma_f32_16x16x32_bf16 v[132:135], v[112:115], v[4:7], v[120:123]
	v_mfma_f32_16x16x32_bf16 v[120:123], v[108:111], v[8:11], v[100:103]
	v_mfma_f32_16x16x32_bf16 v[108:111], v[108:111], v[16:19], v[96:99]
	v_mfma_f32_16x16x32_bf16 v[120:123], v[112:115], v[12:15], v[120:123]
	v_mfma_f32_16x16x32_bf16 v[108:111], v[112:115], v[20:23], v[108:111]
	ds_read_b128 v[144:147], v230 offset:4608
	ds_read_b128 v[148:151], v230 offset:4672
	s_waitcnt lgkmcnt(3)
	v_mfma_f32_16x16x32_bf16 v[112:115], v[116:119], v[0:3], v[104:107]
	s_waitcnt lgkmcnt(2)
	v_mfma_f32_16x16x32_bf16 v[136:139], v[128:131], v[4:7], v[112:115]
	v_mfma_f32_16x16x32_bf16 v[112:115], v[116:119], v[8:11], v[100:103]
	v_mfma_f32_16x16x32_bf16 v[124:127], v[128:131], v[12:15], v[112:115]
	v_mfma_f32_16x16x32_bf16 v[112:115], v[116:119], v[16:19], v[96:99]
	v_mfma_f32_16x16x32_bf16 v[112:115], v[128:131], v[20:23], v[112:115]
	ds_read_b128 v[152:155], v230 offset:6912
	ds_read_b128 v[156:159], v230 offset:6976
	s_waitcnt lgkmcnt(3)
	v_mfma_f32_16x16x32_bf16 v[116:119], v[144:147], v[0:3], v[104:107]
	s_waitcnt lgkmcnt(2)
	v_mfma_f32_16x16x32_bf16 v[140:143], v[148:151], v[4:7], v[116:119]
	v_mfma_f32_16x16x32_bf16 v[116:119], v[144:147], v[8:11], v[100:103]
	v_mfma_f32_16x16x32_bf16 v[128:131], v[148:151], v[12:15], v[116:119]
	v_mfma_f32_16x16x32_bf16 v[116:119], v[144:147], v[16:19], v[96:99]
	v_mfma_f32_16x16x32_bf16 v[116:119], v[148:151], v[20:23], v[116:119]
	s_waitcnt lgkmcnt(1)
	v_mfma_f32_16x16x32_bf16 v[104:107], v[152:155], v[0:3], v[104:107]
	v_mfma_f32_16x16x32_bf16 v[100:103], v[152:155], v[8:11], v[100:103]
	v_mfma_f32_16x16x32_bf16 v[96:99], v[152:155], v[16:19], v[96:99]
	s_waitcnt lgkmcnt(0)
	v_mfma_f32_16x16x32_bf16 v[104:107], v[156:159], v[4:7], v[104:107]
	v_mfma_f32_16x16x32_bf16 v[100:103], v[156:159], v[12:15], v[100:103]
	v_mfma_f32_16x16x32_bf16 v[96:99], v[156:159], v[20:23], v[96:99]
	v_max_f32_e32 v144, v133, v133
	v_max_f32_e32 v145, v132, v132
	v_max_f32_e32 v144, v145, v144
	v_max3_f32 v145, v135, v136, v137
	v_max3_f32 v146, v141, v142, v143
	s_nop 0
	v_max3_f32 v147, v104, v105, v106
	v_max3_f32 v144, v144, v134, v145
	v_max3_f32 v145, v138, v139, v140
	v_max3_f32 v146, v146, v147, v107
	v_max3_f32 v144, v144, v145, v146
	v_max_f32_e32 v145, v121, v121
	v_max_f32_e32 v146, v120, v120
	v_max_f32_e32 v145, v146, v145
	v_max3_f32 v146, v123, v124, v125
	v_max3_f32 v147, v129, v130, v131
	v_max3_f32 v148, v100, v101, v102
	v_max3_f32 v145, v145, v122, v146
	v_max3_f32 v146, v126, v127, v128
	v_max3_f32 v147, v147, v148, v103
	v_max3_f32 v145, v145, v146, v147
	v_max_f32_e32 v146, v109, v109
	v_max_f32_e32 v147, v108, v108
	v_max_f32_e32 v146, v147, v146
	v_max3_f32 v147, v111, v112, v113
	v_max3_f32 v148, v117, v118, v119
	v_max3_f32 v149, v96, v97, v98
	v_max3_f32 v146, v146, v110, v147
	v_max3_f32 v147, v114, v115, v116
	v_max3_f32 v148, v148, v149, v99
	v_max3_f32 v146, v146, v147, v148
	v_mov_b32_e32 v147, v144
	s_nop 1
	v_permlane16_swap_b32_e32 v144, v147
	v_max_f32_e32 v147, v147, v147
	v_max_f32_e32 v144, v144, v144
	v_max_f32_e32 v147, v144, v147
	v_mov_b32_e32 v144, v145
	s_nop 1
	v_permlane16_swap_b32_e32 v145, v144
	v_max_f32_e32 v144, v144, v144
	v_max_f32_e32 v145, v145, v145
	v_max_f32_e32 v145, v145, v144
	v_mov_b32_e32 v144, v146
	s_nop 1
	v_permlane16_swap_b32_e32 v146, v144
	v_max_f32_e32 v144, v144, v144
	v_max_f32_e32 v146, v146, v146
	v_max_f32_e32 v144, v146, v144
	v_mov_b32_e32 v146, v147
	s_nop 1
	v_permlane32_swap_b32_e32 v147, v146
	v_max_f32_e32 v146, v146, v146
	v_max_f32_e32 v147, v147, v147
	v_max_f32_e32 v146, v147, v146
	v_mov_b32_e32 v148, v145
	v_mov_b32_e32 v147, v144
	s_nop 0
	v_permlane32_swap_b32_e32 v145, v148
	v_permlane32_swap_b32_e32 v144, v147
	v_cmp_lt_f32_e32 vcc, s33, v146
	s_mov_b64 s[6:7], 0
	s_mov_b64 s[8:9], 0
	s_and_saveexec_b64 s[18:19], vcc
	v_and_b32_e32 v149, 1, v229
	v_cmp_eq_u32_e32 vcc, 0, v149
	v_cmp_lt_f32_e64 s[4:5], s88, v146
	s_or_b64 s[4:5], vcc, s[4:5]
	s_and_b64 s[8:9], s[4:5], exec
	s_or_b64 exec, exec, s[18:19]
	v_max_f32_e32 v145, v145, v145
	v_max_f32_e32 v148, v148, v148
	v_max_f32_e32 v145, v145, v148
	v_cmp_lt_f32_e32 vcc, s33, v145
	s_and_saveexec_b64 s[18:19], vcc
	v_and_b32_e32 v148, 2, v229
	v_cmp_eq_u32_e32 vcc, 0, v148
	v_cmp_lt_f32_e64 s[4:5], s88, v145
	s_or_b64 s[4:5], vcc, s[4:5]
	s_and_b64 s[6:7], s[4:5], exec
	s_or_b64 exec, exec, s[18:19]
	v_max_f32_e32 v144, v144, v144
	v_max_f32_e32 v147, v147, v147
	v_max_f32_e32 v144, v144, v147
	v_cmp_lt_f32_e32 vcc, s33, v144
	s_mov_b64 s[4:5], 0
	s_and_saveexec_b64 s[18:19], vcc
	v_and_b32_e32 v147, 4, v229
	v_cmp_eq_u32_e32 vcc, 0, v147
	v_cmp_lt_f32_e64 s[4:5], s88, v144
	s_or_b64 s[4:5], vcc, s[4:5]
	s_and_b64 s[4:5], s[4:5], exec
	s_or_b64 exec, exec, s[18:19]
	s_or_b64 s[18:19], s[8:9], s[6:7]
	s_or_b64 s[18:19], s[18:19], s[4:5]
	s_and_b64 vcc, exec, s[18:19]
	s_cbranch_vccz .LBB0_980
; template <bool MASKED>
; __device__ __forceinline__ void qk_softmax(const LAS bf16_t* Kt, const bf16x8 (&qf)[3][2], float (&m)[3], f32x4 (&lacc)[3], f32x4 (&acc)[3][4], unsigned& started,
;                                            bool act, int hi, int lo, int lr, int q, bf16x8 (&pb)[3][2]) {
;     ...
; #pragma unroll
;         for (int r = 0; r < 3; ++r) {
;             const bool st = ((started >> r) & 1u) != 0u;
;             const float dl = need[r] ? mx[r] : 0.f;
;             const float alpha = need[r] ? (st ? __builtin_amdgcn_exp2f(-dl) : 0.f) : 1.f;
;             m[r] += dl;
; #pragma unroll
;             for (int mt = 0; mt < 4; ++mt) s[r][mt] = s[r][mt] - dl;
;             lacc[r] = lacc[r] * alpha;
; #pragma unroll
;             for (int dt = 0; dt < 4; ++dt) acc[r][dt] = acc[r][dt] * alpha;
;             if (need[r]) started |= (1u << r);
;         }
;     }
	v_cndmask_b32_e64 v146, 0, v146, s[8:9]
	v_exp_f32_e64 v147, -v146
	v_and_b32_e32 v148, 1, v229
	v_cmp_eq_u32_e32 vcc, 1, v148
	v_add_f32_e32 v226, v226, v146
	v_sub_f32_e32 v132, v132, v146
	v_cndmask_b32_e32 v147, 0, v147, vcc
	v_sub_f32_e32 v133, v133, v146
	v_sub_f32_e32 v134, v134, v146
	v_sub_f32_e32 v135, v135, v146
	v_sub_f32_e32 v136, v136, v146
	v_sub_f32_e32 v137, v137, v146
	v_sub_f32_e32 v138, v138, v146
	v_sub_f32_e32 v139, v139, v146
	v_sub_f32_e32 v140, v140, v146
	v_sub_f32_e32 v141, v141, v146
	v_sub_f32_e32 v142, v142, v146
	v_sub_f32_e32 v143, v143, v146
	v_sub_f32_e32 v104, v104, v146
	v_sub_f32_e32 v105, v105, v146
	v_sub_f32_e32 v106, v106, v146
	v_sub_f32_e32 v107, v107, v146
	v_cndmask_b32_e64 v146, 1.0, v147, s[8:9]
	v_cndmask_b32_e64 v145, 0, v145, s[6:7]
	v_pk_mul_f32 v[94:95], v[94:95], v[146:147] op_sel_hi:[1,0]
	v_pk_mul_f32 v[92:93], v[92:93], v[146:147] op_sel_hi:[1,0]
	v_pk_mul_f32 v[70:71], v[70:71], v[146:147] op_sel_hi:[1,0]
	v_pk_mul_f32 v[68:69], v[68:69], v[146:147] op_sel_hi:[1,0]
	v_pk_mul_f32 v[66:67], v[66:67], v[146:147] op_sel_hi:[1,0]
	v_pk_mul_f32 v[64:65], v[64:65], v[146:147] op_sel_hi:[1,0]
	v_pk_mul_f32 v[62:63], v[62:63], v[146:147] op_sel_hi:[1,0]
	v_pk_mul_f32 v[60:61], v[60:61], v[146:147] op_sel_hi:[1,0]
	v_pk_mul_f32 v[58:59], v[58:59], v[146:147] op_sel_hi:[1,0]
	v_pk_mul_f32 v[56:57], v[56:57], v[146:147] op_sel_hi:[1,0]
	v_exp_f32_e64 v147, -v145
	v_cndmask_b32_e64 v146, 0, 1, s[8:9]
	v_or_b32_e32 v148, v229, v146
	v_and_b32_e32 v146, 2, v229
	v_cmp_ne_u32_e32 vcc, 0, v146
	v_cndmask_b32_e64 v144, 0, v144, s[4:5]
	v_add_f32_e32 v227, v227, v145
	v_cndmask_b32_e32 v146, 0, v147, vcc
	v_cndmask_b32_e64 v146, 1.0, v146, s[6:7]
	v_sub_f32_e32 v120, v120, v145
	v_sub_f32_e32 v121, v121, v145
	v_sub_f32_e32 v122, v122, v145
	v_sub_f32_e32 v123, v123, v145
	v_sub_f32_e32 v124, v124, v145
	v_sub_f32_e32 v125, v125, v145
	v_sub_f32_e32 v126, v126, v145
	v_sub_f32_e32 v127, v127, v145
	v_sub_f32_e32 v128, v128, v145
	v_sub_f32_e32 v129, v129, v145
	v_sub_f32_e32 v130, v130, v145
	v_sub_f32_e32 v131, v131, v145
	v_sub_f32_e32 v100, v100, v145
	v_sub_f32_e32 v101, v101, v145
	v_sub_f32_e32 v102, v102, v145
	v_sub_f32_e32 v103, v103, v145
	v_pk_mul_f32 v[90:91], v[90:91], v[146:147] op_sel_hi:[1,0]
	v_pk_mul_f32 v[88:89], v[88:89], v[146:147] op_sel_hi:[1,0]
	v_pk_mul_f32 v[54:55], v[54:55], v[146:147] op_sel_hi:[1,0]
	v_pk_mul_f32 v[52:53], v[52:53], v[146:147] op_sel_hi:[1,0]
	v_pk_mul_f32 v[50:51], v[50:51], v[146:147] op_sel_hi:[1,0]
	v_pk_mul_f32 v[48:49], v[48:49], v[146:147] op_sel_hi:[1,0]
	v_pk_mul_f32 v[46:47], v[46:47], v[146:147] op_sel_hi:[1,0]
	v_pk_mul_f32 v[44:45], v[44:45], v[146:147] op_sel_hi:[1,0]
	v_pk_mul_f32 v[42:43], v[42:43], v[146:147] op_sel_hi:[1,0]
	v_pk_mul_f32 v[40:41], v[40:41], v[146:147] op_sel_hi:[1,0]
	v_or_b32_e32 v145, 2, v148
	v_exp_f32_e64 v146, -v144
	v_cndmask_b32_e64 v145, v148, v145, s[6:7]
	v_and_b32_e32 v147, 4, v145
	v_cmp_ne_u32_e32 vcc, 0, v147
	v_add_f32_e32 v228, v228, v144
	v_sub_f32_e32 v108, v108, v144
	v_cndmask_b32_e32 v146, 0, v146, vcc
	v_sub_f32_e32 v109, v109, v144
	v_sub_f32_e32 v110, v110, v144
	v_sub_f32_e32 v111, v111, v144
	v_sub_f32_e32 v112, v112, v144
	v_sub_f32_e32 v113, v113, v144
	v_sub_f32_e32 v114, v114, v144
	v_sub_f32_e32 v115, v115, v144
	v_sub_f32_e32 v116, v116, v144
	v_sub_f32_e32 v117, v117, v144
	v_sub_f32_e32 v118, v118, v144
	v_sub_f32_e32 v119, v119, v144
	v_sub_f32_e32 v96, v96, v144
	v_sub_f32_e32 v97, v97, v144
	v_sub_f32_e32 v98, v98, v144
	v_sub_f32_e32 v99, v99, v144
	v_cndmask_b32_e64 v144, 1.0, v146, s[4:5]
	v_pk_mul_f32 v[86:87], v[86:87], v[144:145] op_sel_hi:[1,0]
	v_pk_mul_f32 v[84:85], v[84:85], v[144:145] op_sel_hi:[1,0]
	v_pk_mul_f32 v[38:39], v[38:39], v[144:145] op_sel_hi:[1,0]
	v_pk_mul_f32 v[36:37], v[36:37], v[144:145] op_sel_hi:[1,0]
	v_pk_mul_f32 v[34:35], v[34:35], v[144:145] op_sel_hi:[1,0]
	v_pk_mul_f32 v[32:33], v[32:33], v[144:145] op_sel_hi:[1,0]
	v_pk_mul_f32 v[30:31], v[30:31], v[144:145] op_sel_hi:[1,0]
	v_pk_mul_f32 v[28:29], v[28:29], v[144:145] op_sel_hi:[1,0]
	v_pk_mul_f32 v[26:27], v[26:27], v[144:145] op_sel_hi:[1,0]
	v_pk_mul_f32 v[24:25], v[24:25], v[144:145] op_sel_hi:[1,0]
	v_or_b32_e32 v144, 4, v145
	v_cndmask_b32_e64 v229, v145, v144, s[4:5]

; __device__ __forceinline__ float xmax16(float v) { const auto r = __builtin_amdgcn_permlane16_swap(__float_as_uint(v), __float_as_uint(v), false, false); return fmaxf(__uint_as_float(r[0]), __uint_as_float(r[1])); }
; __device__ __forceinline__ float xmax32(float v) { const auto r = __builtin_amdgcn_permlane32_swap(__float_as_uint(v), __float_as_uint(v), false, false); return fmaxf(__uint_as_float(r[0]), __uint_as_float(r[1])); }
; #define LAS __attribute__((address_space(3)))
; __device__ __forceinline__ s16x4 vtr(const LAS bf16_t* p) { return __builtin_bit_cast(s16x4, __builtin_amdgcn_ds_read_tr16_b64_v4i16((LAS v4i16_t*)p)); }
; __device__ __forceinline__ void sel_group(const LAS bf16_t* Kt, const LAS bf16_t* Vt, LAS float* S, const bf16x8 qB0, const bf16x8 qB1, int jc, int rc, bool valid, bool masked, int tw64, int lr, int q) {
;     ...
;     float mx = fmaxf(fmaxf(fmaxf(fmaxf(fmaxf(s[0][0], s[0][1]), s[0][2]), fmaxf(fmaxf(s[0][3], s[1][0]), s[1][1])), fmaxf(fmaxf(s[1][2], s[1][3]), s[2][0])), fmaxf(fmaxf(fmaxf(fmaxf(s[2][1], s[2][2]), s[2][3]), fmaxf(fmaxf(s[3][0], s[3][1]), s[3][2])), s[3][3]));
;     mx = pg8::xmax16(mx); mx = pg8::xmax32(mx);
;     const bool need = valid && (mx > -1e29f) && (!st || mx > RESC_THR);
;     const bool anyneed = __builtin_amdgcn_ballot_w64(need) != 0ull;
;     float alpha = 1.f;
;     if (anyneed) {
;         const float dl = need ? mx : 0.f;
;         alpha = need ? (st ? __builtin_amdgcn_exp2f(-dl) : 0.f) : 1.f;
; #pragma unroll
;         for (int mt = 0; mt < 4; ++mt) s[mt] = s[mt] - dl;
;         if (need && q == 0) { Srow[65] = mref + dl; Srow[66] = 1.f; }
;     }
;     ...
;         const LAS bf16_t* vbase = Vt + (4 * q + (lr >> 2)) * 72 + 4 * (lr & 3);
;         const bf16x8 ones = (bf16x8){0x3F80, 0x3F80, 0x3F80, 0x3F80, 0x3F80, 0x3F80, 0x3F80, 0x3F80};
;         s16x4 vv[2][2];
;         vv[0][0] = vtr(vbase); vv[0][1] = vtr(vbase + 16 * 72);
; #pragma unroll
;         for (int it = 0; it < 8; ++it) {
;             const int kk = it >> 2, dt = it & 3;
;             if (it < 7) { const int kk2 = (it + 1) >> 2, dt2 = (it + 1) & 3; vv[(it + 1) & 1][0] = vtr(vbase + (32 * kk2) * 72 + 16 * dt2); vv[(it + 1) & 1][1] = vtr(vbase + (32 * kk2 + 16) * 72 + 16 * dt2); }
;             __builtin_amdgcn_sched_barrier(0);
.LBB0_1067:
	ds_read_b64_tr_b16 v[142:143], v115 offset:18432
	ds_read_b64_tr_b16 v[144:145], v115 offset:20736
	ds_read_b64_tr_b16 v[146:147], v115 offset:18464
	ds_read_b64_tr_b16 v[148:149], v115 offset:20768
	ds_read_b64_tr_b16 v[150:151], v115 offset:18496
	ds_read_b64_tr_b16 v[152:153], v115 offset:20800
	ds_read_b64_tr_b16 v[154:155], v115 offset:18528
	ds_read_b64_tr_b16 v[156:157], v115 offset:20832
	ds_read_b64_tr_b16 v[158:159], v115 offset:23040
	ds_read_b64_tr_b16 v[160:161], v115 offset:25344
	ds_read_b64_tr_b16 v[162:163], v115 offset:23072
	ds_read_b64_tr_b16 v[164:165], v115 offset:25376
	ds_read_b64_tr_b16 v[166:167], v115 offset:23104
	ds_read_b64_tr_b16 v[168:169], v115 offset:25408
	ds_read_b64_tr_b16 v[170:171], v115 offset:23136
	ds_read_b64_tr_b16 v[172:173], v115 offset:25440
	v_max_f32_e32 v80, v65, v65
	v_max_f32_e32 v81, v64, v64
	v_max_f32_e32 v80, v81, v80
	v_max3_f32 v81, v67, v68, v69
	v_max3_f32 v82, v73, v74, v75
	v_max3_f32 v83, v76, v77, v78
	v_max3_f32 v80, v80, v66, v81
	v_max3_f32 v81, v70, v71, v72
	v_max3_f32 v82, v82, v83, v79
	v_max3_f32 v80, v80, v81, v82
	v_mov_b32_e32 v81, v80
	s_nop 1
	v_permlane16_swap_b32_e32 v80, v81
	v_max_f32_e32 v81, v81, v81
	v_max_f32_e32 v80, v80, v80
	v_max_f32_e32 v80, v80, v81
	v_mov_b32_e32 v81, v80
	s_nop 1
	v_permlane32_swap_b32_e32 v80, v81
	v_max_f32_e32 v81, v81, v81
	v_max_f32_e32 v80, v80, v80
	v_max_f32_e32 v80, v80, v81
	v_cmp_lt_f32_e32 vcc, s33, v80
	v_cmp_eq_f32_e64 s[80:81], 0, v86
	s_and_b64 s[4:5], s[76:77], vcc
	v_cmp_lt_f32_e32 vcc, s88, v80
	s_or_b64 s[6:7], s[80:81], vcc
	s_and_b64 s[78:79], s[4:5], s[6:7]
	s_and_b64 vcc, exec, s[78:79]
	s_cselect_b64 s[4:5], -1, 0
	s_cbranch_vccz .LBB0_1071
	v_cndmask_b32_e64 v80, 0, v80, s[78:79]
	s_and_b64 s[12:13], s[68:69], s[78:79]
	s_and_saveexec_b64 s[6:7], s[12:13]
	v_add_f32_e32 v81, v85, v80
	v_add_u32_e32 v82, 0xb504, v119
	ds_write2_b32 v82, v81, v225 offset1:1
	s_or_b64 exec, exec, s[6:7]
	v_exp_f32_e64 v81, -v80
	v_sub_f32_e32 v79, v79, v80
	v_sub_f32_e32 v78, v78, v80
	v_sub_f32_e32 v77, v77, v80
	v_cndmask_b32_e64 v81, v81, 0, s[80:81]
	v_sub_f32_e32 v76, v76, v80
	v_sub_f32_e32 v75, v75, v80
	v_sub_f32_e32 v74, v74, v80
	v_sub_f32_e32 v73, v73, v80
	v_sub_f32_e32 v72, v72, v80
	v_sub_f32_e32 v71, v71, v80
	v_sub_f32_e32 v70, v70, v80
	v_sub_f32_e32 v69, v69, v80
	v_sub_f32_e32 v68, v68, v80
	v_sub_f32_e32 v67, v67, v80
	v_sub_f32_e32 v66, v66, v80
	v_sub_f32_e32 v65, v65, v80
	v_sub_f32_e32 v64, v64, v80
	v_cndmask_b32_e64 v80, 1.0, v81, s[78:79]
	s_branch .LBB0_1072

; __device__ __forceinline__ float xmax16(float v) { const auto r = __builtin_amdgcn_permlane16_swap(__float_as_uint(v), __float_as_uint(v), false, false); return fmaxf(__uint_as_float(r[0]), __uint_as_float(r[1])); }
; __device__ __forceinline__ float xmax32(float v) { const auto r = __builtin_amdgcn_permlane32_swap(__float_as_uint(v), __float_as_uint(v), false, false); return fmaxf(__uint_as_float(r[0]), __uint_as_float(r[1])); }
; __device__ __forceinline__ void sel_group(const LAS bf16_t* Kt, const LAS bf16_t* Vt, LAS float* S, const bf16x8 qB0, const bf16x8 qB1, int jc, int rc, bool valid, bool masked, int tw64, int lr, int q) {
;     ...
;     float mx = fmaxf(fmaxf(fmaxf(fmaxf(fmaxf(s[0][0], s[0][1]), s[0][2]), fmaxf(fmaxf(s[0][3], s[1][0]), s[1][1])), fmaxf(fmaxf(s[1][2], s[1][3]), s[2][0])), fmaxf(fmaxf(fmaxf(fmaxf(s[2][1], s[2][2]), s[2][3]), fmaxf(fmaxf(s[3][0], s[3][1]), s[3][2])), s[3][3]));
;     mx = pg8::xmax16(mx); mx = pg8::xmax32(mx);
;     const bool need = valid && (mx > -1e29f) && (!st || mx > RESC_THR);
;     const bool anyneed = __builtin_amdgcn_ballot_w64(need) != 0ull;
;     float alpha = 1.f;
;     if (anyneed) {
;         const float dl = need ? mx : 0.f;
;         alpha = need ? (st ? __builtin_amdgcn_exp2f(-dl) : 0.f) : 1.f;
; #pragma unroll
;         for (int mt = 0; mt < 4; ++mt) s[mt] = s[mt] - dl;
;         if (need && q == 0) { Srow[65] = mref + dl; Srow[66] = 1.f; }
;     }
.LBB0_1081:
	v_max_f32_e32 v44, v65, v65
	v_max_f32_e32 v45, v64, v64
	v_max_f32_e32 v44, v45, v44
	v_max3_f32 v45, v67, v68, v69
	v_max3_f32 v46, v73, v74, v75
	v_max3_f32 v47, v40, v41, v42
	v_max3_f32 v44, v44, v66, v45
	v_max3_f32 v45, v70, v71, v72
	v_max3_f32 v46, v46, v47, v43
	v_max3_f32 v44, v44, v45, v46
	v_mov_b32_e32 v45, v44
	s_nop 1
	v_permlane16_swap_b32_e32 v44, v45
	v_max_f32_e32 v45, v45, v45
	v_max_f32_e32 v44, v44, v44
	v_max_f32_e32 v44, v44, v45
	v_mov_b32_e32 v45, v44
	s_nop 1
	v_permlane32_swap_b32_e32 v44, v45
	v_max_f32_e32 v45, v45, v45
	v_max_f32_e32 v44, v44, v44
	v_max_f32_e32 v44, v44, v45
	v_cmp_lt_f32_e32 vcc, s33, v44
	v_cmp_eq_f32_e64 s[78:79], 0, v78
	s_and_b64 s[4:5], s[74:75], vcc
	v_cmp_lt_f32_e32 vcc, s88, v44
	s_or_b64 s[6:7], s[78:79], vcc
	s_and_b64 s[76:77], s[4:5], s[6:7]
	s_and_b64 vcc, exec, s[76:77]
	s_cselect_b64 s[4:5], -1, 0
	s_cbranch_vccz .LBB0_1085
	v_cndmask_b32_e64 v44, 0, v44, s[76:77]
	s_and_b64 s[12:13], s[68:69], s[76:77]
	s_and_saveexec_b64 s[6:7], s[12:13]
	v_add_f32_e32 v45, v77, v44
	v_add_u32_e32 v46, 0xb504, v79
	ds_write2_b32 v46, v45, v225 offset1:1
	s_or_b64 exec, exec, s[6:7]
	v_exp_f32_e64 v45, -v44
	v_sub_f32_e32 v43, v43, v44
	v_sub_f32_e32 v42, v42, v44
	v_sub_f32_e32 v41, v41, v44
	v_cndmask_b32_e64 v45, v45, 0, s[78:79]
	v_sub_f32_e32 v40, v40, v44
	v_sub_f32_e32 v75, v75, v44
	v_sub_f32_e32 v74, v74, v44
	v_sub_f32_e32 v73, v73, v44
	v_sub_f32_e32 v72, v72, v44
	v_sub_f32_e32 v71, v71, v44
	v_sub_f32_e32 v70, v70, v44
	v_sub_f32_e32 v69, v69, v44
	v_sub_f32_e32 v68, v68, v44
	v_sub_f32_e32 v67, v67, v44
	v_sub_f32_e32 v66, v66, v44
	v_sub_f32_e32 v65, v65, v44
	v_sub_f32_e32 v64, v64, v44
	v_cndmask_b32_e64 v78, 1.0, v45, s[76:77]
	s_branch .LBB0_1086

; __device__ __forceinline__ float xmax16(float v) { const auto r = __builtin_amdgcn_permlane16_swap(__float_as_uint(v), __float_as_uint(v), false, false); return fmaxf(__uint_as_float(r[0]), __uint_as_float(r[1])); }
; __device__ __forceinline__ float xmax32(float v) { const auto r = __builtin_amdgcn_permlane32_swap(__float_as_uint(v), __float_as_uint(v), false, false); return fmaxf(__uint_as_float(r[0]), __uint_as_float(r[1])); }
; __device__ __forceinline__ void sel_group(const LAS bf16_t* Kt, const LAS bf16_t* Vt, LAS float* S, const bf16x8 qB0, const bf16x8 qB1, int jc, int rc, bool valid, bool masked, int tw64, int lr, int q) {
;     ...
;     float mx = fmaxf(fmaxf(fmaxf(fmaxf(fmaxf(s[0][0], s[0][1]), s[0][2]), fmaxf(fmaxf(s[0][3], s[1][0]), s[1][1])), fmaxf(fmaxf(s[1][2], s[1][3]), s[2][0])), fmaxf(fmaxf(fmaxf(fmaxf(s[2][1], s[2][2]), s[2][3]), fmaxf(fmaxf(s[3][0], s[3][1]), s[3][2])), s[3][3]));
;     mx = pg8::xmax16(mx); mx = pg8::xmax32(mx);
;     const bool need = valid && (mx > -1e29f) && (!st || mx > RESC_THR);
;     const bool anyneed = __builtin_amdgcn_ballot_w64(need) != 0ull;
;     float alpha = 1.f;
;     if (anyneed) {
;         const float dl = need ? mx : 0.f;
;         alpha = need ? (st ? __builtin_amdgcn_exp2f(-dl) : 0.f) : 1.f;
; #pragma unroll
;         for (int mt = 0; mt < 4; ++mt) s[mt] = s[mt] - dl;
;         if (need && q == 0) { Srow[65] = mref + dl; Srow[66] = 1.f; }
;     }
.LBB0_1095:
	v_max_f32_e32 v36, v57, v57
	v_max_f32_e32 v37, v56, v56
	v_max_f32_e32 v36, v37, v36
	v_max3_f32 v37, v59, v60, v61
	v_max3_f32 v38, v65, v66, v67
	v_max3_f32 v39, v32, v33, v34
	v_max3_f32 v36, v36, v58, v37
	v_max3_f32 v37, v62, v63, v64
	v_max3_f32 v38, v38, v39, v35
	v_max3_f32 v36, v36, v37, v38
	v_mov_b32_e32 v37, v36
	s_nop 1
	v_permlane16_swap_b32_e32 v36, v37
	v_max_f32_e32 v37, v37, v37
	v_max_f32_e32 v36, v36, v36
	v_max_f32_e32 v36, v36, v37
	v_mov_b32_e32 v37, v36
	s_nop 1
	v_permlane32_swap_b32_e32 v36, v37
	v_max_f32_e32 v37, v37, v37
	v_max_f32_e32 v36, v36, v36
	v_max_f32_e32 v36, v36, v37
	v_cmp_lt_f32_e32 vcc, s33, v36
	v_cmp_eq_f32_e64 s[74:75], 0, v70
	s_and_b64 s[4:5], s[70:71], vcc
	v_cmp_lt_f32_e32 vcc, s88, v36
	s_or_b64 s[6:7], s[74:75], vcc
	s_and_b64 s[72:73], s[4:5], s[6:7]
	s_and_b64 vcc, exec, s[72:73]
	s_cselect_b64 s[4:5], -1, 0
	s_cbranch_vccz .LBB0_1099
	v_cndmask_b32_e64 v36, 0, v36, s[72:73]
	s_and_b64 s[10:11], s[68:69], s[72:73]
	s_and_saveexec_b64 s[6:7], s[10:11]
	v_add_f32_e32 v37, v69, v36
	v_add_u32_e32 v38, 0xb504, v71
	ds_write2_b32 v38, v37, v225 offset1:1
	s_or_b64 exec, exec, s[6:7]
	v_exp_f32_e64 v37, -v36
	v_sub_f32_e32 v35, v35, v36
	v_sub_f32_e32 v34, v34, v36
	v_sub_f32_e32 v33, v33, v36
	v_cndmask_b32_e64 v37, v37, 0, s[74:75]
	v_sub_f32_e32 v32, v32, v36
	v_sub_f32_e32 v67, v67, v36
	v_sub_f32_e32 v66, v66, v36
	v_sub_f32_e32 v65, v65, v36
	v_sub_f32_e32 v64, v64, v36
	v_sub_f32_e32 v63, v63, v36
	v_sub_f32_e32 v62, v62, v36
	v_sub_f32_e32 v61, v61, v36
	v_sub_f32_e32 v60, v60, v36
	v_sub_f32_e32 v59, v59, v36
	v_sub_f32_e32 v58, v58, v36
	v_sub_f32_e32 v57, v57, v36
	v_sub_f32_e32 v56, v56, v36
	v_cndmask_b32_e64 v70, 1.0, v37, s[72:73]
	s_branch .LBB0_1100
